# c4 + diff attention loop: PV MFMAs of previous tile deferred and interleaved with QK/softmax VALU of current tile (in-wave pipelining)
# baseline (speedup 1.0000x reference)
; template <int DK, int MODE, bool OUTF32> ...
;     ...
;     const int tid = opaque_tid(), wave = tid >> 6, lane = tid & 63, c = lane & 31, hi = lane >> 5;
;     const int rg = wave >> 1, kh = wave & 1;
;     const int qw0 = q0 + 32 * rg, qrow = qw0 + c, cw = qw0 >> 6;
;     int t_lo = 0;
;     if (MODE == 1) { t_lo = (q0 >> 6) - 8; if (t_lo < 0) t_lo = 0; }
;     const int t_hi = ((q0 + 127) >> 6) + 1;
;     bf16x8 qf[NKS];
; #pragma unroll
;     for (int s = 0; s < NKS; ++s) qf[s] = *(const bf16x8*)(Qh + (size_t)qrow * DK + 16 * s + 8 * hi);
;     float cq = 0.f;
;     if (MODE == 0) cq = cumh[qrow];
; #pragma unroll
;     for (int s = 0; s < NKS; ++s) asm volatile("" : "+v"(qf[s]));
;     asm volatile("" : "+v"(cq));
;     if (MODE == 1) { for (int i = tid; i < 257; i += NTHR) ((float*)(a_lds + OFF_RB))[i] = relb[i] * LOG2E; }
;     float cso = 0.f;
;     const float* offs = (const float*)(a_lds + OFF_RB);
;     if (MODE == 0) {
;         if (wave == 0) {
;             const float v0 = relb[lane], v1 = relb[64 + lane];
;             float s0 = v0, s1 = v1;
; #pragma unroll
;             for (int d_ = 1; d_ < 64; d_ <<= 1) {
;                 const float t0 = __int_as_float(__builtin_amdgcn_ds_bpermute((lane - d_) * 4, __float_as_int(s0)));
; __device__ __forceinline__ void attn_odd_phase(const bf16_t* __restrict__ att, bf16_t* __restrict__ Ob, float* __restrict__ A12, unsigned* ctr) {
;     ...
;         const int j = 31 - item / 48, r = item % 48;
;         if (r < 16) {
;             const int bh = r, b = bh >> 3, h = bh & 7;
;             attn_item<192, 2, false>(att + (size_t)bh * S * 192, att + MHSZ + (size_t)bh * S * 192, att + 2 * MHSZ + (size_t)bh * 128 * S,
;                                      Ob + (size_t)b * S * D + h * 128, D, j * 128, nullptr, nullptr, SC192);
;         } else {
;             const int v = r - 16, b = v >> 4, vh2 = v & 15, vh = vh2 >> 1, half = vh2 & 1, hd = vh >> 1, comp = vh & 1;
;             attn_item<128, 2, true>(att + 2 * MHSZ + EHSZ + (size_t)(b * 8 + vh) * S * 128, att + 2 * MHSZ + 2 * EHSZ + (size_t)(b * 8 + vh) * S * 128,
;                                     att + 2 * MHSZ + 3 * EHSZ + ((size_t)(b * 4 + hd) * 256 + half * 128) * S,
;                                     A12 + (size_t)b * S * D + hd * 512 + comp * 256 + half * 128, D, j * 128, nullptr, nullptr, SC128);
.LBB0_939:
	s_mov_b32 s12, 0xd5555555
	v_mul_hi_i32 v2, v1, s12
	v_lshrrev_b32_e32 v4, 31, v2
	v_ashrrev_i32_e32 v2, 3, v2
	s_mov_b32 s12, 0x2aaaaaab
	v_add3_u32 v2, v2, v4, 31
	v_mul_hi_i32 v4, v1, s12
	v_lshrrev_b32_e32 v5, 31, v4
	v_lshrrev_b32_e32 v4, 3, v4
	v_add_u32_e32 v4, v4, v5
	v_mul_lo_u32 v4, v4, 48
	v_sub_u32_e32 v156, v1, v4
	v_lshlrev_b32_e32 v4, 7, v2
	v_cmp_lt_i32_e32 vcc, 15, v156
	v_lshrrev_b32_e32 v1, 6, v4
	s_and_saveexec_b64 s[12:13], vcc
	s_xor_b64 s[46:47], exec, s[12:13]
	s_cbranch_execz .LBB0_955
	v_add_u32_e32 v2, -16, v156
	v_lshrrev_b32_e32 v2, 4, v2
	v_bfe_u32 v5, v156, 1, 3
	v_mov_b32_e32 v120, v0
	v_lshl_or_b32 v6, v2, 3, v5
	v_mov_b32_e32 v7, v3
	v_ashrrev_i32_e32 v5, 2, v120
	v_and_b32_e32 v5, 0xffffffe0, v5
	v_and_b32_e32 v121, 31, v120
	v_add_u32_e32 v123, v5, v4
	v_or_b32_e32 v166, v123, v121
	v_lshlrev_b64 v[6:7], 20, v[6:7]
	v_ashrrev_i32_e32 v167, 31, v166
	v_lshl_add_u64 v[8:9], s[78:79], 0, v[6:7]
	v_bfe_u32 v122, v120, 5, 1
	v_lshlrev_b64 v[4:5], 8, v[166:167]
	v_lshl_add_u64 v[4:5], v[8:9], 0, v[4:5]
	v_lshlrev_b32_e32 v164, 4, v122
	v_mov_b32_e32 v165, v3
	v_lshl_add_u64 v[4:5], v[4:5], 0, v[164:165]
	flat_load_dwordx4 v[112:115], v[4:5]
	flat_load_dwordx4 v[108:111], v[4:5] offset:32
	flat_load_dwordx4 v[104:107], v[4:5] offset:64
	flat_load_dwordx4 v[100:103], v[4:5] offset:96
	flat_load_dwordx4 v[96:99], v[4:5] offset:128
	flat_load_dwordx4 v[92:95], v[4:5] offset:160
	flat_load_dwordx4 v[88:91], v[4:5] offset:192
	flat_load_dwordx4 v[84:87], v[4:5] offset:224
	v_lshrrev_b32_e32 v165, 1, v156
	v_lshlrev_b32_e32 v4, 7, v156
	v_bfe_u32 v169, v165, 1, 2
	v_mov_b32_e32 v5, v3
	v_and_b32_e32 v168, 0x80, v4
	v_lshl_or_b32 v4, v2, 2, v169
	v_ashrrev_i32_e32 v10, 31, v120
	v_add_u32_e32 v11, 0x200, v120
	v_lshlrev_b64 v[4:5], 21, v[4:5]
	v_lshrrev_b32_e32 v10, 28, v10
	v_ashrrev_i32_e32 v13, 31, v11
	v_mov_b32_e32 v9, v3
	v_lshlrev_b32_e32 v8, 13, v168
	v_lshl_add_u64 v[70:71], s[52:53], 0, v[6:7]
	v_lshl_add_u64 v[4:5], s[54:55], 0, v[4:5]
	v_add_u32_e32 v6, v120, v10
	v_lshrrev_b32_e32 v7, 28, v13
	v_ashrrev_i32_e32 v68, 3, v120
	v_lshl_add_u64 v[74:75], v[4:5], 0, v[8:9]
	v_and_b32_e32 v4, -16, v6
	v_add_u32_e32 v5, v11, v7
	v_ashrrev_i32_e32 v69, 31, v68
	v_ashrrev_i32_e32 v76, 4, v6
	v_sub_u32_e32 v124, v120, v4
	v_and_b32_e32 v6, -16, v5
	v_lshlrev_b32_e32 v12, 4, v120
	v_lshlrev_b64 v[72:73], 13, v[68:69]
	v_ashrrev_i32_e32 v78, 4, v5
	v_ashrrev_i32_e32 v77, 31, v76
	v_sub_u32_e32 v125, v11, v6
	v_lshlrev_b32_e32 v6, 3, v124
	v_mov_b32_e32 v171, v3
	v_and_b32_e32 v170, 0x70, v12
	v_lshl_add_u64 v[4:5], v[74:75], 0, v[72:73]
	v_lshlrev_b64 v[80:81], 8, v[76:77]
	v_ashrrev_i32_e32 v79, 31, v78
	v_ashrrev_i32_e32 v7, 31, v6
	v_lshlrev_b32_e32 v10, 3, v125
	v_lshl_add_u64 v[4:5], v[4:5], 0, v[170:171]
	v_lshl_add_u64 v[8:9], v[70:71], 0, v[80:81]
	v_lshlrev_b64 v[82:83], 8, v[78:79]
	s_mov_b32 s12, 0x80000
	v_lshlrev_b64 v[116:117], 1, v[6:7]
	v_ashrrev_i32_e32 v11, 31, v10
	v_mov_b32_e32 v14, v3
	v_add_co_u32_e32 v12, vcc, s12, v4
	v_lshl_add_u64 v[6:7], v[70:71], 0, v[82:83]
	v_lshl_add_u64 v[8:9], v[8:9], 0, v[116:117]
	v_lshlrev_b64 v[118:119], 1, v[10:11]
	v_addc_co_u32_e32 v13, vcc, 0, v5, vcc
	v_lshl_add_u64 v[6:7], v[6:7], 0, v[118:119]
	v_ashrrev_i32_e32 v171, 6, v120
	s_movk_i32 s13, 0x88
	v_and_b32_e32 v180, 1, v171
	v_mul_lo_u32 v185, v68, s13
	v_mad_u32_u24 v68, v121, s13, 0
	s_movk_i32 s13, 0x110
	v_and_b32_e32 v178, 63, v120
	v_lshlrev_b32_e32 v69, 3, v122
	s_waitcnt vmcnt(0) lgkmcnt(0)
	global_load_dwordx4 v[52:55], v[8:9], off
	global_load_dwordx4 v[56:59], v[6:7], off
	global_load_dwordx4 v[60:63], v[4:5], off
	global_load_dwordx4 v[64:67], v[12:13], off
	v_lshlrev_b32_e32 v120, 6, v180
	v_mul_lo_u32 v188, v76, s13
	v_or_b32_e32 v72, v72, v170
	v_lshlrev_b32_e32 v189, 4, v124
	v_mov_b32_e32 v18, v3
	v_mov_b32_e32 v19, v3
	v_add3_u32 v77, 0, v185, v170
	v_lshl_or_b32 v79, v180, 5, v121
	v_add3_u32 v184, v68, v69, v120
	v_lshl_add_u64 v[68:69], v[70:71], 0, s[10:11]
	v_mul_lo_u32 v190, v78, s13
	v_lshl_add_u64 v[70:71], v[74:75], 0, v[72:73]
	v_add3_u32 v74, 0, v188, v189
	v_lshlrev_b32_e32 v191, 4, v125
	s_mov_b64 s[10:11], 0x80080
	v_mov_b32_e32 v4, v3
	v_mov_b32_e32 v5, v3
	v_mov_b32_e32 v6, v3
	v_mov_b32_e32 v7, v3
	v_mov_b32_e32 v8, v3
	v_mov_b32_e32 v9, v3
	v_mov_b32_e32 v10, v3
	v_mov_b32_e32 v11, v3
	v_mov_b32_e32 v12, v3
	v_mov_b32_e32 v13, v3
	v_mov_b32_e32 v14, v3
	v_mov_b32_e32 v15, v3
	v_mov_b32_e32 v16, v3
	v_mov_b32_e32 v17, v3
	v_mov_b64_e32 v[50:51], v[18:19]
	v_mov_b64_e32 v[34:35], v[18:19]
	v_add_u32_e32 v121, 0xc800, v77
	v_add_u32_e32 v77, 0xea00, v77
	v_mul_u32_u24_e32 v79, 0x110, v79
	v_lshl_add_u64 v[172:173], v[70:71], 0, s[10:11]
	v_add3_u32 v75, 0, v190, v191
	v_lshl_add_u64 v[70:71], v[80:81], 0, v[116:117]
	v_lshl_add_u64 v[72:73], v[82:83], 0, v[118:119]
	s_mov_b32 s12, 0
	v_or_b32_e32 v182, 1, v1
	v_mov_b32_e32 v179, 0
	v_mov_b32_e32 v181, 0xf149f2ca
	s_mov_b64 s[42:43], 0
	v_mov_b64_e32 v[48:49], v[16:17]
	v_mov_b64_e32 v[46:47], v[14:15]
	v_mov_b64_e32 v[44:45], v[12:13]
	v_mov_b64_e32 v[42:43], v[10:11]
	v_mov_b64_e32 v[40:41], v[8:9]
	v_mov_b64_e32 v[38:39], v[6:7]
	v_mov_b64_e32 v[36:37], v[4:5]
	v_mov_b64_e32 v[32:33], v[16:17]
	v_mov_b64_e32 v[30:31], v[14:15]
	v_mov_b64_e32 v[28:29], v[12:13]
	v_mov_b64_e32 v[26:27], v[10:11]
	v_mov_b64_e32 v[24:25], v[8:9]
	v_mov_b64_e32 v[22:23], v[6:7]
	v_mov_b64_e32 v[20:21], v[4:5]
	v_add_u32_e32 v186, 0x2200, v185
	v_ashrrev_i32_e32 v187, 6, v123
	v_add3_u32 v183, 0, v79, v164
	v_lshl_add_u64 v[174:175], v[68:69], 0, v[70:71]
	v_lshl_add_u64 v[176:177], v[68:69], 0, v[72:73]
	s_waitcnt vmcnt(3)
; __device__ __forceinline__ unsigned cvtpk(float lo, float hi) { return __builtin_bit_cast(unsigned, __builtin_convertvector(f32x2_cv{lo, hi}, bf16x2_cv)); }
; __device__ __forceinline__ float dot2bf(unsigned w, unsigned x, float acc) { return __builtin_amdgcn_fdot2_f32_bf16(__builtin_bit_cast(bf16x2_t, w), __builtin_bit_cast(bf16x2_t, x), acc, false); }
; template <int DK, int MODE, bool OUTF32> ...
;     ...
;             if (!__all(mx - m <= 8.f)) {
;                 const float mn = fmaxf(m, mx), alpha = __builtin_amdgcn_exp2f(m - mn);
;                 m = mn; l *= alpha;
; #pragma unroll
;                 for (int db = 0; db < 4; ++db)
; #pragma unroll
;                     for (int r = 0; r < 16; ++r) o[db][r] *= alpha;
;             }
; #pragma unroll
;             for (int r = 0; r < 16; ++r) p[r] = __builtin_amdgcn_exp2f((MODE == 2) ? fmaf(p[r], sc2, -m) : (p[r] - m));
;             bf16x8 pb0, pb1;
;             { const unsigned w0 = cvtpk(p[0], p[1]), w1 = cvtpk(p[2], p[3]), w2 = cvtpk(p[4], p[5]), w3 = cvtpk(p[6], p[7]);
;               const uint4 u = make_uint4(w0, w1, w2, w3); pb0 = *reinterpret_cast<const bf16x8*>(&u); }
;             { const unsigned w0 = cvtpk(p[8], p[9]), w1 = cvtpk(p[10], p[11]), w2 = cvtpk(p[12], p[13]), w3 = cvtpk(p[14], p[15]);
;               const uint4 u = make_uint4(w0, w1, w2, w3); pb1 = *reinterpret_cast<const bf16x8*>(&u); }
;             {
;                 const uint4 ua = *reinterpret_cast<const uint4*>(&pb0), ub = *reinterpret_cast<const uint4*>(&pb1);
;                 float ps = 0.f, ps2 = 0.f;
;                 ps = dot2bf(ua.x, 0x3f803f80u, ps); ps2 = dot2bf(ua.y, 0x3f803f80u, ps2); ps = dot2bf(ua.z, 0x3f803f80u, ps); ps2 = dot2bf(ua.w, 0x3f803f80u, ps2);
;                 ps = dot2bf(ub.x, 0x3f803f80u, ps); ps2 = dot2bf(ub.y, 0x3f803f80u, ps2); ps = dot2bf(ub.z, 0x3f803f80u, ps); ps2 = dot2bf(ub.w, 0x3f803f80u, ps2);
;                 l += ps + ps2;
	ds_write_b128 v74, v[52:55]
	s_waitcnt vmcnt(2)
	ds_write_b128 v75, v[56:59]
	s_waitcnt vmcnt(1)
	ds_write2_b64 v121, v[60:61], v[62:63] offset1:1
	s_waitcnt vmcnt(0)
	ds_write2_b64 v77, v[64:65], v[66:67] offset1:1
	v_mov_b64_e32 v[66:67], v[18:19]
	v_mov_b64_e32 v[64:65], v[16:17]
	v_mov_b64_e32 v[62:63], v[14:15]
	v_mov_b64_e32 v[60:61], v[12:13]
	v_mov_b64_e32 v[58:59], v[10:11]
	v_mov_b64_e32 v[56:57], v[8:9]
	v_mov_b64_e32 v[54:55], v[6:7]
	v_mov_b64_e32 v[52:53], v[4:5]
	v_mov_b32_e32 v132, 0
	v_mov_b32_e32 v133, 0
	v_mov_b32_e32 v134, 0
	v_mov_b32_e32 v135, 0
	v_mov_b32_e32 v136, 0
	v_mov_b32_e32 v137, 0
	v_mov_b32_e32 v138, 0
	v_mov_b32_e32 v139, 0
	v_mov_b32_e32 v140, 0
	v_mov_b32_e32 v141, 0
	v_mov_b32_e32 v142, 0
	v_mov_b32_e32 v143, 0
	v_mov_b32_e32 v144, 0
	v_mov_b32_e32 v145, 0
	v_mov_b32_e32 v146, 0
	v_mov_b32_e32 v147, 0
	v_mov_b32_e32 v148, 0
	v_mov_b32_e32 v149, 0
	v_mov_b32_e32 v150, 0
	v_mov_b32_e32 v151, 0
	v_mov_b32_e32 v152, 0
	v_mov_b32_e32 v153, 0
	v_mov_b32_e32 v154, 0
	v_mov_b32_e32 v155, 0
	v_mov_b32_e32 v156, 0
	v_mov_b32_e32 v157, 0
	v_mov_b32_e32 v158, 0
	v_mov_b32_e32 v159, 0
	v_mov_b32_e32 v160, 0
	v_mov_b32_e32 v161, 0
	v_mov_b32_e32 v162, 0
	v_mov_b32_e32 v163, 0
	v_mov_b32_e32 v232, 0
	v_mov_b32_e32 v233, 0
	v_mov_b32_e32 v234, 0
	v_mov_b32_e32 v235, 0
	v_mov_b32_e32 v236, 0
	v_mov_b32_e32 v237, 0
	v_mov_b32_e32 v238, 0
	v_mov_b32_e32 v239, 0
	s_waitcnt lgkmcnt(0)
	s_barrier
	s_branch .LBB0_943
.Ldp_rare:
	v_mfma_f32_32x32x16_bf16 v[52:67], v[136:139], v[236:239], v[52:67]
	ds_read2_b64 v[136:139], v242 offset0:4 offset1:6
	v_mfma_f32_32x32x16_bf16 v[20:35], v[144:147], v[236:239], v[20:35]
	ds_read2_b64 v[144:147], v243 offset0:36 offset1:38
	v_mfma_f32_32x32x16_bf16 v[36:51], v[152:155], v[236:239], v[36:51]
	ds_read2_b64 v[152:155], v244 offset0:68 offset1:70
	v_mfma_f32_32x32x16_bf16 v[4:19], v[156:159], v[236:239], v[4:19]
	ds_read2_b64 v[156:159], v245 offset0:100 offset1:102
	v_max_f32_e32 v192, v192, v192
	v_max_f32_e32 v193, v181, v181
	v_max_f32_e32 v193, v193, v192
	v_sub_f32_e32 v181, v181, v193
	v_exp_f32_e32 v192, v181
	v_mov_b32_e32 v181, v193
	s_nop 15
	v_pk_mul_f32 v[66:67], v[66:67], v[192:193] op_sel_hi:[1,0]
	v_pk_mul_f32 v[64:65], v[64:65], v[192:193] op_sel_hi:[1,0]
	v_pk_mul_f32 v[62:63], v[62:63], v[192:193] op_sel_hi:[1,0]
	v_pk_mul_f32 v[60:61], v[60:61], v[192:193] op_sel_hi:[1,0]
	v_pk_mul_f32 v[58:59], v[58:59], v[192:193] op_sel_hi:[1,0]
	v_pk_mul_f32 v[56:57], v[56:57], v[192:193] op_sel_hi:[1,0]
	v_pk_mul_f32 v[54:55], v[54:55], v[192:193] op_sel_hi:[1,0]
	v_pk_mul_f32 v[52:53], v[52:53], v[192:193] op_sel_hi:[1,0]
	v_pk_mul_f32 v[34:35], v[34:35], v[192:193] op_sel_hi:[1,0]
	v_pk_mul_f32 v[32:33], v[32:33], v[192:193] op_sel_hi:[1,0]
	v_pk_mul_f32 v[30:31], v[30:31], v[192:193] op_sel_hi:[1,0]
	v_pk_mul_f32 v[28:29], v[28:29], v[192:193] op_sel_hi:[1,0]
	v_pk_mul_f32 v[26:27], v[26:27], v[192:193] op_sel_hi:[1,0]
	v_pk_mul_f32 v[24:25], v[24:25], v[192:193] op_sel_hi:[1,0]
	v_pk_mul_f32 v[22:23], v[22:23], v[192:193] op_sel_hi:[1,0]
	v_pk_mul_f32 v[20:21], v[20:21], v[192:193] op_sel_hi:[1,0]
	v_pk_mul_f32 v[50:51], v[50:51], v[192:193] op_sel_hi:[1,0]
	v_pk_mul_f32 v[48:49], v[48:49], v[192:193] op_sel_hi:[1,0]
	v_pk_mul_f32 v[46:47], v[46:47], v[192:193] op_sel_hi:[1,0]
	v_pk_mul_f32 v[44:45], v[44:45], v[192:193] op_sel_hi:[1,0]
	v_pk_mul_f32 v[42:43], v[42:43], v[192:193] op_sel_hi:[1,0]
	v_pk_mul_f32 v[40:41], v[40:41], v[192:193] op_sel_hi:[1,0]
	v_pk_mul_f32 v[38:39], v[38:39], v[192:193] op_sel_hi:[1,0]
	v_pk_mul_f32 v[36:37], v[36:37], v[192:193] op_sel_hi:[1,0]
	v_pk_mul_f32 v[18:19], v[18:19], v[192:193] op_sel_hi:[1,0]
	v_pk_mul_f32 v[16:17], v[16:17], v[192:193] op_sel_hi:[1,0]
	v_pk_mul_f32 v[14:15], v[14:15], v[192:193] op_sel_hi:[1,0]
	v_pk_mul_f32 v[12:13], v[12:13], v[192:193] op_sel_hi:[1,0]
	v_pk_mul_f32 v[10:11], v[10:11], v[192:193] op_sel_hi:[1,0]
	v_pk_mul_f32 v[8:9], v[8:9], v[192:193] op_sel_hi:[1,0]
	v_pk_mul_f32 v[6:7], v[6:7], v[192:193] op_sel_hi:[1,0]
	v_pk_mul_f32 v[4:5], v[4:5], v[192:193] op_sel_hi:[1,0]
	v_mul_f32_e32 v179, v179, v192
	v_fma_f32 v68, v68, s24, -v181
	v_fma_f32 v69, v69, s24, -v181
	v_fma_f32 v70, v70, s24, -v181
	v_fma_f32 v71, v71, s24, -v181
	v_fma_f32 v72, v72, s24, -v181
	v_fma_f32 v73, v73, s24, -v181
	v_fma_f32 v76, v76, s24, -v181
	v_fma_f32 v77, v77, s24, -v181
	v_exp_f32_e32 v68, v68
	v_exp_f32_e32 v69, v69
	v_exp_f32_e32 v70, v70
	v_exp_f32_e32 v71, v71
	v_exp_f32_e32 v72, v72
	v_exp_f32_e32 v73, v73
	v_fma_f32 v74, v74, s24, -v181
	v_fma_f32 v75, v75, s24, -v181
	v_exp_f32_e32 v76, v76
	v_exp_f32_e32 v77, v77
	v_exp_f32_e32 v74, v74
	v_exp_f32_e32 v75, v75
	v_fma_f32 v78, v78, s24, -v181
	v_fma_f32 v79, v79, s24, -v181
	v_exp_f32_e32 v78, v78
	v_exp_f32_e32 v79, v79
	v_fma_f32 v80, v80, s24, -v181
	v_fma_f32 v81, v81, s24, -v181
	v_fma_f32 v82, v82, s24, -v181
	v_fma_f32 v83, v83, s24, -v181
	v_exp_f32_e32 v80, v80
	v_exp_f32_e32 v81, v81
	v_exp_f32_e32 v82, v82
	v_exp_f32_e32 v83, v83
	v_cvt_pk_bf16_f32 v232, v68, v69
	v_cvt_pk_bf16_f32 v233, v70, v71
	v_cvt_pk_bf16_f32 v234, v72, v73
	v_cvt_pk_bf16_f32 v236, v76, v77
	v_mov_b32_e32 v76, 0
	v_mov_b32_e32 v77, 0
	v_cvt_pk_bf16_f32 v235, v74, v75
	v_dot2c_f32_bf16_e32 v76, 0x3f803f80, v232
	v_dot2c_f32_bf16_e32 v77, 0x3f803f80, v233
	v_cvt_pk_bf16_f32 v237, v78, v79
	v_dot2c_f32_bf16_e32 v76, 0x3f803f80, v234
	v_dot2c_f32_bf16_e32 v77, 0x3f803f80, v235
	v_cvt_pk_bf16_f32 v238, v80, v81
	v_cvt_pk_bf16_f32 v239, v82, v83
	v_dot2c_f32_bf16_e32 v76, 0x3f803f80, v236
	v_dot2c_f32_bf16_e32 v77, 0x3f803f80, v237
	v_dot2c_f32_bf16_e32 v76, 0x3f803f80, v238
	v_dot2c_f32_bf16_e32 v77, 0x3f803f80, v239
	s_nop 2
	v_add_f32_e32 v76, v76, v77
	s_nop 0
	v_add_f32_e32 v179, v179, v76
	s_branch .Ldp_tail
.Ldp_inact:
	s_or_b64 exec, exec, s[50:51]
	v_mfma_f32_32x32x16_bf16 v[52:67], v[132:135], v[232:235], v[52:67]
	v_mfma_f32_32x32x16_bf16 v[20:35], v[140:143], v[232:235], v[20:35]
	v_mfma_f32_32x32x16_bf16 v[36:51], v[148:151], v[232:235], v[36:51]
	v_mfma_f32_32x32x16_bf16 v[4:19], v[160:163], v[232:235], v[4:19]
	v_mfma_f32_32x32x16_bf16 v[52:67], v[136:139], v[236:239], v[52:67]
	v_mfma_f32_32x32x16_bf16 v[20:35], v[144:147], v[236:239], v[20:35]
	v_mfma_f32_32x32x16_bf16 v[36:51], v[152:155], v[236:239], v[36:51]
	v_mfma_f32_32x32x16_bf16 v[4:19], v[156:159], v[236:239], v[4:19]
	v_mov_b32_e32 v232, 0
	v_mov_b32_e32 v233, 0
	v_mov_b32_e32 v234, 0
	v_mov_b32_e32 v235, 0
	v_mov_b32_e32 v236, 0
	v_mov_b32_e32 v237, 0
	v_mov_b32_e32 v238, 0
	v_mov_b32_e32 v239, 0
	v_add_co_u32_e32 v240, vcc, 0xfff80000, v172
	global_load_dwordx4 v[120:123], v[174:175], off
	global_load_dwordx4 v[116:119], v[176:177], off
	v_addc_co_u32_e32 v241, vcc, -1, v173, vcc
	global_load_dwordx4 v[128:131], v[240:241], off
	global_load_dwordx4 v[124:127], v[172:173], off
	s_branch .Ldp_tail
.LBB0_943:
	s_and_b32 s13, s12, 1
	v_cmp_le_i32_e32 vcc, s12, v187
	s_and_saveexec_b64 s[50:51], vcc
	s_cbranch_execz .Ldp_inact
	s_mul_i32 s14, s13, 0x4400
	v_add_u32_e32 v72, s14, v183
	ds_read_b128 v[68:71], v72
	ds_read_b128 v[224:227], v72 offset:32
	ds_read_b128 v[228:231], v72 offset:64
	ds_read_b128 v[192:195], v72 offset:96
	ds_read_b128 v[208:211], v72 offset:128
	ds_read_b128 v[212:215], v72 offset:160
	ds_read_b128 v[216:219], v72 offset:192
	ds_read_b128 v[220:223], v72 offset:224
	v_mfma_f32_32x32x16_bf16 v[52:67], v[132:135], v[232:235], v[52:67]
	v_add_u32_e32 v196, s14, v184
	v_add_u32_e32 v242, 0xc800, v196
	v_add_u32_e32 v243, 0xd800, v196
	v_mfma_f32_32x32x16_bf16 v[20:35], v[140:143], v[232:235], v[20:35]
	v_add_u32_e32 v244, 0xe800, v196
	v_add_u32_e32 v245, 0xf800, v196
	v_add_co_u32_e32 v240, vcc, 0xfff80000, v172
	global_load_dwordx4 v[120:123], v[174:175], off
	global_load_dwordx4 v[116:119], v[176:177], off
	v_addc_co_u32_e32 v241, vcc, -1, v173, vcc
	global_load_dwordx4 v[128:131], v[240:241], off
	global_load_dwordx4 v[124:127], v[172:173], off
	ds_read2_b64 v[132:135], v242 offset1:2
	ds_read2_b64 v[140:143], v243 offset0:32 offset1:34
	s_waitcnt lgkmcnt(9)
	v_mfma_f32_32x32x16_bf16 v[68:83], v[68:71], v[112:115], 0
	s_waitcnt lgkmcnt(8)
	v_mfma_f32_32x32x16_bf16 v[68:83], v[224:227], v[108:111], v[68:83]
	s_waitcnt lgkmcnt(7)
	v_mfma_f32_32x32x16_bf16 v[68:83], v[228:231], v[104:107], v[68:83]
	s_waitcnt lgkmcnt(6)
	v_mfma_f32_32x32x16_bf16 v[68:83], v[192:195], v[100:103], v[68:83]
	s_waitcnt lgkmcnt(5)
	v_mfma_f32_32x32x16_bf16 v[68:83], v[208:211], v[96:99], v[68:83]
	s_waitcnt lgkmcnt(4)
	v_mfma_f32_32x32x16_bf16 v[68:83], v[212:215], v[92:95], v[68:83]
	s_waitcnt lgkmcnt(3)
	v_mfma_f32_32x32x16_bf16 v[68:83], v[216:219], v[88:91], v[68:83]
	s_waitcnt lgkmcnt(2)
	v_mfma_f32_32x32x16_bf16 v[68:83], v[220:223], v[84:87], v[68:83]
	v_mfma_f32_32x32x16_bf16 v[36:51], v[148:151], v[232:235], v[36:51]
	ds_read2_b64 v[148:151], v244 offset0:64 offset1:66
	v_mfma_f32_32x32x16_bf16 v[4:19], v[160:163], v[232:235], v[4:19]
	ds_read2_b64 v[160:163], v245 offset0:96 offset1:98
	s_nop 7
	v_max_f32_e32 v192, v69, v69
	v_max_f32_e32 v193, v68, v68
	v_max_f32_e32 v192, v193, v192
	v_max3_f32 v192, v192, v70, v71
	v_max3_f32 v192, v192, v72, v73
	v_max3_f32 v192, v192, v74, v75
	v_max3_f32 v192, v192, v76, v77
	v_max3_f32 v192, v192, v78, v79
	v_max3_f32 v192, v192, v80, v81
	v_max3_f32 v192, v192, v82, v83
	v_mul_f32_e32 v192, 0x3e0293ee, v192
	v_mov_b32_e32 v193, v192
	s_nop 1
	v_permlane32_swap_b32_e32 v192, v193
	v_max_f32_e32 v193, v193, v193
	v_max_f32_e32 v192, v192, v192
	v_max_f32_e32 v192, v192, v193
	v_sub_f32_e32 v193, v192, v181
	s_mov_b32 s14, 0x41000000
	v_cmp_ge_f32_e32 vcc, s14, v193
	s_cmp_eq_u64 vcc, exec
	s_cbranch_scc0 .Ldp_rare
	v_fma_f32 v68, v68, s24, -v181
	v_fma_f32 v69, v69, s24, -v181
	v_fma_f32 v70, v70, s24, -v181
	v_fma_f32 v71, v71, s24, -v181
	v_mfma_f32_32x32x16_bf16 v[52:67], v[136:139], v[236:239], v[52:67]
	ds_read2_b64 v[136:139], v242 offset0:4 offset1:6
	v_fma_f32 v72, v72, s24, -v181
	v_fma_f32 v73, v73, s24, -v181
	v_fma_f32 v76, v76, s24, -v181
	v_fma_f32 v77, v77, s24, -v181
	v_exp_f32_e32 v68, v68
	v_exp_f32_e32 v69, v69
	v_exp_f32_e32 v70, v70
	v_exp_f32_e32 v71, v71
	v_mfma_f32_32x32x16_bf16 v[20:35], v[144:147], v[236:239], v[20:35]
	ds_read2_b64 v[144:147], v243 offset0:36 offset1:38
	v_exp_f32_e32 v72, v72
	v_exp_f32_e32 v73, v73
	v_fma_f32 v74, v74, s24, -v181
	v_fma_f32 v75, v75, s24, -v181
	v_exp_f32_e32 v76, v76
	v_exp_f32_e32 v77, v77
	v_exp_f32_e32 v74, v74
	v_exp_f32_e32 v75, v75
	v_mfma_f32_32x32x16_bf16 v[36:51], v[152:155], v[236:239], v[36:51]
	ds_read2_b64 v[152:155], v244 offset0:68 offset1:70
	v_fma_f32 v78, v78, s24, -v181
	v_fma_f32 v79, v79, s24, -v181
	v_exp_f32_e32 v78, v78
	v_exp_f32_e32 v79, v79
	v_fma_f32 v80, v80, s24, -v181
	v_fma_f32 v81, v81, s24, -v181
	v_fma_f32 v82, v82, s24, -v181
	v_mfma_f32_32x32x16_bf16 v[4:19], v[156:159], v[236:239], v[4:19]
	ds_read2_b64 v[156:159], v245 offset0:100 offset1:102
	v_fma_f32 v83, v83, s24, -v181
	v_exp_f32_e32 v80, v80
	v_exp_f32_e32 v81, v81
	v_exp_f32_e32 v82, v82
	v_exp_f32_e32 v83, v83
	v_cvt_pk_bf16_f32 v232, v68, v69
	v_cvt_pk_bf16_f32 v233, v70, v71
	v_cvt_pk_bf16_f32 v234, v72, v73
	v_cvt_pk_bf16_f32 v236, v76, v77
	v_mov_b32_e32 v76, 0
	v_mov_b32_e32 v77, 0
	v_cvt_pk_bf16_f32 v235, v74, v75
	v_dot2c_f32_bf16_e32 v76, 0x3f803f80, v232
	v_dot2c_f32_bf16_e32 v77, 0x3f803f80, v233
	v_cvt_pk_bf16_f32 v237, v78, v79
	v_dot2c_f32_bf16_e32 v76, 0x3f803f80, v234
	v_dot2c_f32_bf16_e32 v77, 0x3f803f80, v235
	v_cvt_pk_bf16_f32 v238, v80, v81
	v_cvt_pk_bf16_f32 v239, v82, v83
	v_dot2c_f32_bf16_e32 v76, 0x3f803f80, v236
	v_dot2c_f32_bf16_e32 v77, 0x3f803f80, v237
	v_dot2c_f32_bf16_e32 v76, 0x3f803f80, v238
	v_dot2c_f32_bf16_e32 v77, 0x3f803f80, v239
	s_nop 2
	v_add_f32_e32 v76, v76, v77
	s_nop 0
	v_add_f32_e32 v179, v179, v76
; template <int DK, int MODE, bool OUTF32> ...
;     ...
;     for (int t = t_lo; t < t_hi; ++t) {
;         const int cur = (t - t_lo) & 1;
;         if (t + 1 < t_hi) A_ISSUE(t + 1);
;         bool act;
;         if (MODE == 0) act = (64 * t + 32 * kh) <= (qw0 + 31);
;         else if (MODE == 1) act = (t <= cw) && (t >= cw - 8);
;         else act = (t <= cw);
;         if (act) {
;             f32x16 p;
; #pragma unroll
;             for (int r = 0; r < 16; ++r) p[r] = 0.f;
;             const unsigned char* kb = a_lds + cur * KBUF + (32 * kh + c) * KP + hi * 16;
;             constexpr bool HOISTK = true;
;             bf16x8 kf[NKS];
;             if (HOISTK) {
; #pragma unroll
;                 for (int s = 0; s < NKS; ++s) kf[s] = *(const bf16x8*)(kb + s * 32);
;             }
;             const unsigned char* vb = a_lds + OFF_V + cur * VBUF + c * VP + (32 * kh + 4 * hi) * 2;
;             bf16x8 vf[8];
;     ...
;             constexpr bool HOISTV = (DK == 128) && (MODE == 2 || MODE == 1);
;             if (HOISTV) A_VREADS(0, 3);
;             if (HOISTK) __builtin_amdgcn_sched_barrier(0);
; #pragma unroll
;             for (int s = 0; s < NKS; ++s) p = __builtin_amdgcn_mfma_f32_32x32x16_bf16(HOISTK ? kf[s] : *(const bf16x8*)(kb + s * 32), qf[s], p, 0, 0, 0);
;             if (HOISTV) { A_VREADS(3, 4); __builtin_amdgcn_sched_barrier(0); }
;             if (MODE == 0) {
;                 const float* ckp = (const float*)(a_lds + OFF_CK + cur * 256) + 32 * kh + 4 * hi;
; #pragma unroll
;                 for (int g = 0; g < 4; ++g) {
;                     const float4 ck = *(const float4*)(ckp + 8 * g);
;                     p[4 * g + 0] = fmaf(p[4 * g + 0], sc2, cq - ck.x); p[4 * g + 1] = fmaf(p[4 * g + 1], sc2, cq - ck.y);
;                     p[4 * g + 2] = fmaf(p[4 * g + 2], sc2, cq - ck.z); p[4 * g + 3] = fmaf(p[4 * g + 3], sc2, cq - ck.w);
;                 }
;                 if (64 * t + 32 * kh + 31 > qw0) {
;                     const int kbase = 64 * t + 32 * kh + 4 * hi;
; #pragma unroll
;                     for (int r = 0; r < 16; ++r) if (kbase + (r & 3) + 8 * (r >> 2) > qrow) p[r] = NEGINF;
;                 }
;             } else if (MODE == 1) {
;                 const float* rb = (const float*)(a_lds + OFF_RB);
;                 if (t <= cw - 3) {
;     ...
;         if (t + 1 < t_hi) A_WRITE(cur ^ 1);
;         __syncthreads();
.Ldp_tail:
	s_or_b64 exec, exec, s[50:51]
	s_xor_b32 s13, s13, 1
	s_mulk_i32 s13, 0x4400
	s_add_i32 s13, s13, 0
	v_add3_u32 v68, s13, v188, v189
	s_waitcnt vmcnt(3)
	ds_write_b128 v68, v[120:123]
	v_add3_u32 v68, s13, v190, v191
	s_waitcnt vmcnt(2)
	ds_write_b128 v68, v[116:119]
	v_add_u32_e32 v68, s13, v185
	s_mov_b32 s14, 0xc800
	v_add3_u32 v68, v68, v170, s14
	s_add_i32 s12, s12, 1
	s_waitcnt vmcnt(1)
	ds_write2_b64 v68, v[128:129], v[130:131] offset1:1
	v_add_u32_e32 v68, s13, v186
	v_add3_u32 v68, v68, v170, s14
	s_mov_b64 s[14:15], 0x4000
	v_cmp_eq_u32_e32 vcc, s12, v182
	v_lshl_add_u64 v[172:173], v[172:173], 0, s[88:89]
	v_lshl_add_u64 v[176:177], v[176:177], 0, s[14:15]
	s_or_b64 s[42:43], vcc, s[42:43]
	s_mov_b64 s[10:11], 0x4000
	v_lshl_add_u64 v[174:175], v[174:175], 0, s[14:15]
	s_waitcnt vmcnt(0)
	ds_write2_b64 v68, v[124:125], v[126:127] offset1:1
	s_waitcnt lgkmcnt(0)
	s_barrier
	s_andn2_b64 exec, exec, s[42:43]
	s_cbranch_execnz .LBB0_943
.LBB0_946:
	s_or_b64 exec, exec, s[42:43]
	v_mfma_f32_32x32x16_bf16 v[52:67], v[132:135], v[232:235], v[52:67]
	v_mfma_f32_32x32x16_bf16 v[20:35], v[140:143], v[232:235], v[20:35]
	v_mfma_f32_32x32x16_bf16 v[36:51], v[148:151], v[232:235], v[36:51]
	v_mfma_f32_32x32x16_bf16 v[4:19], v[160:163], v[232:235], v[4:19]
	v_mfma_f32_32x32x16_bf16 v[52:67], v[136:139], v[236:239], v[52:67]
	v_mfma_f32_32x32x16_bf16 v[20:35], v[144:147], v[236:239], v[20:35]
	v_mfma_f32_32x32x16_bf16 v[36:51], v[152:155], v[236:239], v[36:51]
	v_mfma_f32_32x32x16_bf16 v[4:19], v[156:159], v[236:239], v[4:19]
	v_cmp_lt_i32_e32 vcc, v1, v187
	s_and_saveexec_b64 s[42:43], vcc
	s_cbranch_execz .LBB0_950
	ds_read_b128 v[68:71], v183 offset:17408
	ds_read_b128 v[140:143], v183 offset:17440
	ds_read_b128 v[144:147], v183 offset:17472
	ds_read_b128 v[148:151], v183 offset:17504
	ds_read_b128 v[152:155], v183 offset:17536
	ds_read_b128 v[156:159], v183 offset:17568
	ds_read_b128 v[160:163], v183 offset:17600
	ds_read_b128 v[172:175], v183 offset:17632
	v_add_u32_e32 v1, 0xc800, v184
	v_add_u32_e32 v72, 0x4000, v1
	ds_read2_b64 v[116:119], v72 offset0:128 offset1:130
	ds_read2_b64 v[120:123], v72 offset0:132 offset1:134
	v_add_u32_e32 v72, 0x5000, v1
	ds_read2_b64 v[124:127], v72 offset0:160 offset1:162
	ds_read2_b64 v[128:131], v72 offset0:164 offset1:166
	v_add_u32_e32 v72, 0x6000, v1
	ds_read2_b64 v[132:135], v72 offset0:192 offset1:194
	ds_read2_b64 v[136:139], v72 offset0:196 offset1:198
	s_waitcnt lgkmcnt(13)
	v_mfma_f32_32x32x16_bf16 v[68:83], v[68:71], v[112:115], 0
	v_add_u32_e32 v1, 0x7000, v1
	s_waitcnt lgkmcnt(12)
	v_mfma_f32_32x32x16_bf16 v[68:83], v[140:143], v[108:111], v[68:83]
	s_waitcnt lgkmcnt(11)
	v_mfma_f32_32x32x16_bf16 v[68:83], v[144:147], v[104:107], v[68:83]
	s_waitcnt lgkmcnt(10)
	v_mfma_f32_32x32x16_bf16 v[68:83], v[148:151], v[100:103], v[68:83]
	s_waitcnt lgkmcnt(9)
	v_mfma_f32_32x32x16_bf16 v[68:83], v[152:155], v[96:99], v[68:83]
	s_waitcnt lgkmcnt(8)
	v_mfma_f32_32x32x16_bf16 v[68:83], v[156:159], v[92:95], v[68:83]
	s_waitcnt lgkmcnt(7)
	v_mfma_f32_32x32x16_bf16 v[68:83], v[160:163], v[88:91], v[68:83]
	ds_read2_b64 v[92:95], v1 offset0:224 offset1:226
	ds_read2_b64 v[88:91], v1 offset0:228 offset1:230
	s_waitcnt lgkmcnt(8)
	v_mfma_f32_32x32x16_bf16 v[68:83], v[172:175], v[84:87], v[68:83]
	s_nop 11
	v_max_f32_e32 v1, v69, v69
	v_max_f32_e32 v84, v68, v68
	v_max_f32_e32 v1, v84, v1
	v_max3_f32 v1, v1, v70, v71
	v_max3_f32 v1, v1, v72, v73
	v_max3_f32 v1, v1, v74, v75
	v_max3_f32 v1, v1, v76, v77
	v_max3_f32 v1, v1, v78, v79
	v_max3_f32 v1, v1, v80, v81
	v_max3_f32 v1, v1, v82, v83
	v_mul_f32_e32 v1, 0x3e0293ee, v1
	v_mov_b32_e32 v84, v1
	s_nop 1
	v_permlane32_swap_b32_e32 v1, v84
	v_max_f32_e32 v84, v84, v84
	v_max_f32_e32 v1, v1, v1
	v_max_f32_e32 v1, v1, v84
	v_sub_f32_e32 v84, v1, v181
	s_mov_b32 s12, 0x41000000
	v_cmp_ge_f32_e32 vcc, s12, v84
	s_cmp_eq_u64 vcc, exec
	s_cbranch_scc1 .LBB0_949
	v_max_f32_e32 v1, v1, v1
	v_max_f32_e32 v84, v181, v181
	v_max_f32_e32 v1, v84, v1
	v_sub_f32_e32 v84, v181, v1
	v_exp_f32_e32 v84, v84
	v_mov_b32_e32 v181, v1
	v_pk_mul_f32 v[66:67], v[66:67], v[84:85] op_sel_hi:[1,0]
	v_pk_mul_f32 v[64:65], v[64:65], v[84:85] op_sel_hi:[1,0]
	v_pk_mul_f32 v[62:63], v[62:63], v[84:85] op_sel_hi:[1,0]
	v_pk_mul_f32 v[60:61], v[60:61], v[84:85] op_sel_hi:[1,0]
	v_pk_mul_f32 v[58:59], v[58:59], v[84:85] op_sel_hi:[1,0]
	v_pk_mul_f32 v[56:57], v[56:57], v[84:85] op_sel_hi:[1,0]
	v_pk_mul_f32 v[54:55], v[54:55], v[84:85] op_sel_hi:[1,0]
	v_pk_mul_f32 v[52:53], v[52:53], v[84:85] op_sel_hi:[1,0]
	v_pk_mul_f32 v[34:35], v[34:35], v[84:85] op_sel_hi:[1,0]
	v_pk_mul_f32 v[32:33], v[32:33], v[84:85] op_sel_hi:[1,0]
	v_pk_mul_f32 v[30:31], v[30:31], v[84:85] op_sel_hi:[1,0]
	v_pk_mul_f32 v[28:29], v[28:29], v[84:85] op_sel_hi:[1,0]
	v_pk_mul_f32 v[26:27], v[26:27], v[84:85] op_sel_hi:[1,0]
	v_pk_mul_f32 v[24:25], v[24:25], v[84:85] op_sel_hi:[1,0]
	v_pk_mul_f32 v[22:23], v[22:23], v[84:85] op_sel_hi:[1,0]
	v_pk_mul_f32 v[20:21], v[20:21], v[84:85] op_sel_hi:[1,0]
	v_pk_mul_f32 v[50:51], v[50:51], v[84:85] op_sel_hi:[1,0]
	v_pk_mul_f32 v[48:49], v[48:49], v[84:85] op_sel_hi:[1,0]
	v_pk_mul_f32 v[46:47], v[46:47], v[84:85] op_sel_hi:[1,0]
	v_pk_mul_f32 v[44:45], v[44:45], v[84:85] op_sel_hi:[1,0]
	v_pk_mul_f32 v[42:43], v[42:43], v[84:85] op_sel_hi:[1,0]
	v_pk_mul_f32 v[40:41], v[40:41], v[84:85] op_sel_hi:[1,0]
	v_pk_mul_f32 v[38:39], v[38:39], v[84:85] op_sel_hi:[1,0]
	v_pk_mul_f32 v[36:37], v[36:37], v[84:85] op_sel_hi:[1,0]
	v_pk_mul_f32 v[18:19], v[18:19], v[84:85] op_sel_hi:[1,0]
	v_pk_mul_f32 v[16:17], v[16:17], v[84:85] op_sel_hi:[1,0]
	v_pk_mul_f32 v[14:15], v[14:15], v[84:85] op_sel_hi:[1,0]
	v_pk_mul_f32 v[12:13], v[12:13], v[84:85] op_sel_hi:[1,0]
	v_pk_mul_f32 v[10:11], v[10:11], v[84:85] op_sel_hi:[1,0]
	v_pk_mul_f32 v[8:9], v[8:9], v[84:85] op_sel_hi:[1,0]
	v_pk_mul_f32 v[6:7], v[6:7], v[84:85] op_sel_hi:[1,0]
	v_pk_mul_f32 v[4:5], v[4:5], v[84:85] op_sel_hi:[1,0]
	v_mul_f32_e32 v179, v179, v84
